# nt cache hint on the read-once x row loads of the conversion phase and on the y loads and final stores of the last norm phase
# speedup vs baseline: 1.0022x; 1.0022x over previous
; #define GAS __attribute__((address_space(1)))
; __device__ __forceinline__ unsigned pk2(float lo, float hi) { return pg8::cvt_pk_bf16(lo, hi); }
; __device__ __forceinline__ void p0_row(const float* xrow, bf16* orow, float* rs, int lane) {
;     float s = 0.f; GAS v2u* o8 = (GAS v2u*)orow + lane;
;     if (xrow) { const GAS f32x4* xr = (const GAS f32x4*)xrow + lane;
; #pragma unroll
;         for (int j = 0; j < 16; ++j) { const f32x4 v = xr[64 * j]; s += (v.x * v.x + v.y * v.y) + (v.z * v.z + v.w * v.w); v2u w; w.x = pk2(v.x, v.y); w.y = pk2(v.z, v.w); o8[64 * j] = w; }
;     } else {
; __global__ void __launch_bounds__(NTHR, 2) fwd_kernel(Args args) {
;     ...
;         for (int m = gw; m < MP; m += NGW) {
;             const float* src = m < 256 ? x_sample + (size_t)m * 4096 : (m < 272 ? meta_tokens + (size_t)(m - 256) * 4096 : (m < MV ? x_prompt + (size_t)(m - 272) * 4096 : nullptr));
;             p0_row(src, XB + (size_t)m * 4096, RS1 + m, lane);
;         }
.LBB0_293:
	v_lshl_add_u64 v[26:27], s[10:11], 0, v[24:25]
	s_cmp_lg_u64 s[8:9], 0
	v_lshl_add_u64 v[28:29], v[26:27], 0, s[28:29]
	s_cbranch_scc0 .LBB0_298
	s_add_u32 s98, s8, 0x1000
	s_addc_u32 s99, s9, 0
	s_add_u32 s100, s8, 0x2000
	s_addc_u32 s101, s9, 0
	s_add_u32 vcc_lo, s8, 0x3000
	s_addc_u32 vcc_hi, s9, 0
	global_load_dwordx4 v[80:83], v22, s[8:9] nt
	global_load_dwordx4 v[84:87], v22, s[8:9] offset:1024 nt
	global_load_dwordx4 v[88:91], v22, s[8:9] offset:2048 nt
	global_load_dwordx4 v[92:95], v22, s[8:9] offset:3072 nt
	global_load_dwordx4 v[96:99], v22, s[98:99] nt
	global_load_dwordx4 v[100:103], v22, s[98:99] offset:1024 nt
	global_load_dwordx4 v[104:107], v22, s[98:99] offset:2048 nt
	global_load_dwordx4 v[108:111], v22, s[98:99] offset:3072 nt
	global_load_dwordx4 v[112:115], v22, s[100:101] nt
	global_load_dwordx4 v[116:119], v22, s[100:101] offset:1024 nt
	global_load_dwordx4 v[120:123], v22, s[100:101] offset:2048 nt
	global_load_dwordx4 v[124:127], v22, s[100:101] offset:3072 nt
	global_load_dwordx4 v[128:131], v22, vcc nt
	global_load_dwordx4 v[132:135], v22, vcc offset:1024 nt
	global_load_dwordx4 v[136:139], v22, vcc offset:2048 nt
	global_load_dwordx4 v[140:143], v22, vcc offset:3072 nt
	s_waitcnt vmcnt(15)
	v_mov_b64_e32 v[2:3], v[80:81]
	v_mov_b64_e32 v[4:5], v[82:83]
	v_cvt_pk_bf16_f32 v6, v2, v3
	v_cvt_pk_bf16_f32 v7, v4, v5
	global_store_dwordx2 v[28:29], v[6:7], off
	s_waitcnt vmcnt(15)
	v_mov_b64_e32 v[6:7], v[84:85]
	v_mov_b64_e32 v[8:9], v[86:87]
	v_add_co_u32_e32 v44, vcc, s3, v26
	v_cvt_pk_bf16_f32 v10, v6, v7
	v_cvt_pk_bf16_f32 v11, v8, v9
	v_lshl_add_u64 v[60:61], s[8:9], 0, v[22:23]
	v_addc_co_u32_e32 v45, vcc, 0, v27, vcc
	global_store_dwordx2 v[44:45], v[10:11], off offset:512
	s_waitcnt vmcnt(15)
	v_mov_b64_e32 v[10:11], v[88:89]
	v_mov_b64_e32 v[12:13], v[90:91]
	v_cvt_pk_bf16_f32 v14, v10, v11
	v_cvt_pk_bf16_f32 v15, v12, v13
	global_store_dwordx2 v[44:45], v[14:15], off offset:1024
	s_waitcnt vmcnt(15)
	v_mov_b64_e32 v[14:15], v[92:93]
	v_mov_b64_e32 v[16:17], v[94:95]
	v_add_co_u32_e32 v56, vcc, s5, v60
	v_cvt_pk_bf16_f32 v18, v14, v15
	v_cvt_pk_bf16_f32 v19, v16, v17
	global_store_dwordx2 v[44:45], v[18:19], off offset:1536
	v_addc_co_u32_e32 v57, vcc, 0, v61, vcc
	s_waitcnt vmcnt(15)
	v_mov_b64_e32 v[18:19], v[96:97]
	v_mov_b64_e32 v[20:21], v[98:99]
	v_add_co_u32_e32 v40, vcc, s4, v60
	v_cvt_pk_bf16_f32 v32, v18, v19
	v_cvt_pk_bf16_f32 v33, v20, v21
	global_store_dwordx2 v[44:45], v[32:33], off offset:2048
	v_addc_co_u32_e32 v41, vcc, 0, v61, vcc
	s_waitcnt vmcnt(15)
	v_mov_b64_e32 v[32:33], v[100:101]
	v_mov_b64_e32 v[34:35], v[102:103]
	v_cvt_pk_bf16_f32 v36, v32, v33
	v_cvt_pk_bf16_f32 v37, v34, v35
	global_store_dwordx2 v[44:45], v[36:37], off offset:2560
	s_waitcnt vmcnt(15)
	v_mov_b64_e32 v[36:37], v[104:105]
	v_mov_b64_e32 v[38:39], v[106:107]
	v_cvt_pk_bf16_f32 v42, v36, v37
	v_cvt_pk_bf16_f32 v43, v38, v39
	global_store_dwordx2 v[44:45], v[42:43], off offset:3072
	s_waitcnt vmcnt(15)
	v_mov_b64_e32 v[40:41], v[108:109]
	v_mov_b64_e32 v[42:43], v[110:111]
	v_cvt_pk_bf16_f32 v46, v40, v41
	v_cvt_pk_bf16_f32 v47, v42, v43
	global_store_dwordx2 v[44:45], v[46:47], off offset:3584
	v_add_co_u32_e32 v72, vcc, s21, v26
	s_waitcnt vmcnt(15)
	v_mov_b64_e32 v[44:45], v[112:113]
	v_mov_b64_e32 v[46:47], v[114:115]
	s_nop 0
	v_addc_co_u32_e32 v73, vcc, 0, v27, vcc
	v_cvt_pk_bf16_f32 v48, v44, v45
	v_cvt_pk_bf16_f32 v49, v46, v47
	global_store_dwordx2 v[72:73], v[48:49], off
	s_waitcnt vmcnt(15)
	v_mov_b64_e32 v[48:49], v[116:117]
	v_mov_b64_e32 v[50:51], v[118:119]
	v_cvt_pk_bf16_f32 v52, v48, v49
	v_cvt_pk_bf16_f32 v53, v50, v51
	global_store_dwordx2 v[72:73], v[52:53], off offset:512
	s_waitcnt vmcnt(15)
	v_mov_b64_e32 v[52:53], v[120:121]
	v_mov_b64_e32 v[54:55], v[122:123]
	v_cvt_pk_bf16_f32 v58, v52, v53
	v_cvt_pk_bf16_f32 v59, v54, v55
	global_store_dwordx2 v[72:73], v[58:59], off offset:1024
	s_waitcnt vmcnt(15)
	v_mov_b64_e32 v[56:57], v[124:125]
	v_mov_b64_e32 v[58:59], v[126:127]
	v_add_co_u32_e32 v74, vcc, s34, v60
	v_cvt_pk_bf16_f32 v60, v56, v57
	s_nop 0
	v_addc_co_u32_e32 v75, vcc, 0, v61, vcc
	v_cvt_pk_bf16_f32 v61, v58, v59
	global_store_dwordx2 v[72:73], v[60:61], off offset:1536
	s_waitcnt vmcnt(15)
	v_mov_b64_e32 v[60:61], v[128:129]
	v_mov_b64_e32 v[62:63], v[130:131]
	v_cvt_pk_bf16_f32 v64, v60, v61
	v_cvt_pk_bf16_f32 v65, v62, v63
	global_store_dwordx2 v[72:73], v[64:65], off offset:2048
	s_waitcnt vmcnt(15)
; __device__ __forceinline__ unsigned pk2(float lo, float hi) { return pg8::cvt_pk_bf16(lo, hi); }
; __device__ __forceinline__ void p0_row(const float* xrow, bf16* orow, float* rs, int lane) {
;     ...
;         for (int j = 0; j < 16; ++j) { const f32x4 v = xr[64 * j]; s += (v.x * v.x + v.y * v.y) + (v.z * v.z + v.w * v.w); v2u w; w.x = pk2(v.x, v.y); w.y = pk2(v.z, v.w); o8[64 * j] = w; }
;     } else {
; #pragma unroll
;         for (int j = 0; j < 16; ++j) { v2u w; w.x = 0u; w.y = 0u; o8[64 * j] = w; } }
;     s = wave_sum(s);
;     if (lane == 0) *rs = 1.f / sqrtf(s * (1.f / 4096.f) + EPS);
	v_mov_b64_e32 v[64:65], v[132:133]
	v_mov_b64_e32 v[66:67], v[134:135]
	v_cvt_pk_bf16_f32 v68, v64, v65
	v_cvt_pk_bf16_f32 v69, v66, v67
	global_store_dwordx2 v[72:73], v[68:69], off offset:2560
	s_waitcnt vmcnt(15)
	v_mov_b64_e32 v[68:69], v[136:137]
	v_mov_b64_e32 v[70:71], v[138:139]
	v_pk_mul_f32 v[4:5], v[4:5], v[4:5]
	v_pk_mul_f32 v[2:3], v[2:3], v[2:3]
	v_pk_mul_f32 v[6:7], v[6:7], v[6:7]
	v_pk_mov_b32 v[76:77], v[2:3], v[4:5] op_sel:[1,0]
	v_mov_b32_e32 v3, v5
	v_pk_mul_f32 v[4:5], v[8:9], v[8:9]
	v_pk_add_f32 v[2:3], v[76:77], v[2:3]
	v_pk_mov_b32 v[8:9], v[6:7], v[4:5] op_sel:[1,0]
	v_mov_b32_e32 v7, v5
	v_pk_add_f32 v[4:5], v[8:9], v[6:7]
	v_pk_add_f32 v[2:3], v[2:3], v[2:3] op_sel:[0,1] op_sel_hi:[1,0]
	v_pk_add_f32 v[4:5], v[4:5], v[4:5] op_sel:[0,1] op_sel_hi:[1,0]
	v_mul_f32_e32 v6, v11, v11
	v_pk_fma_f32 v[6:7], v[10:11], v[10:11], v[6:7] op_sel_hi:[1,1,0]
	v_mul_f32_e32 v8, v13, v13
	v_mul_f32_e32 v3, v14, v14
	v_mul_f32_e32 v5, v15, v15
	v_pk_add_f32 v[10:11], v[2:3], v[4:5]
	v_cvt_pk_bf16_f32 v2, v68, v69
	v_cvt_pk_bf16_f32 v3, v70, v71
	global_store_dwordx2 v[72:73], v[2:3], off offset:3072
	s_waitcnt vmcnt(15)
	v_mov_b64_e32 v[2:3], v[140:141]
	v_mov_b64_e32 v[4:5], v[142:143]
	v_pk_fma_f32 v[8:9], v[12:13], v[12:13], v[8:9] op_sel_hi:[1,1,0]
	v_mul_f32_e32 v7, v16, v16
	v_mul_f32_e32 v9, v17, v17
	v_pk_add_f32 v[6:7], v[6:7], v[8:9]
	v_pk_mul_f32 v[8:9], v[20:21], v[20:21]
	v_pk_add_f32 v[6:7], v[10:11], v[6:7]
	v_pk_mul_f32 v[10:11], v[18:19], v[18:19]
	v_pk_add_f32 v[6:7], v[6:7], v[6:7] op_sel:[0,1] op_sel_hi:[1,0]
	v_pk_mov_b32 v[12:13], v[10:11], v[8:9] op_sel:[1,0]
	v_mov_b32_e32 v11, v9
	v_pk_add_f32 v[8:9], v[12:13], v[10:11]
	v_mul_f32_e32 v10, v33, v33
	v_mul_f32_e32 v12, v35, v35
	v_pk_add_f32 v[8:9], v[8:9], v[8:9] op_sel:[0,1] op_sel_hi:[1,0]
	v_pk_fma_f32 v[10:11], v[32:33], v[32:33], v[10:11] op_sel_hi:[1,1,0]
	v_pk_fma_f32 v[12:13], v[34:35], v[34:35], v[12:13] op_sel_hi:[1,1,0]
	v_mul_f32_e32 v7, v36, v36
	v_mul_f32_e32 v9, v37, v37
	v_mul_f32_e32 v11, v38, v38
	v_mul_f32_e32 v13, v39, v39
	v_pk_add_f32 v[6:7], v[6:7], v[8:9]
	v_pk_add_f32 v[8:9], v[10:11], v[12:13]
	v_pk_mul_f32 v[10:11], v[40:41], v[40:41]
	v_pk_add_f32 v[6:7], v[6:7], v[8:9]
	v_pk_mul_f32 v[8:9], v[42:43], v[42:43]
	v_pk_add_f32 v[6:7], v[6:7], v[6:7] op_sel:[0,1] op_sel_hi:[1,0]
	v_pk_mov_b32 v[12:13], v[10:11], v[8:9] op_sel:[1,0]
	v_mov_b32_e32 v11, v9
	v_pk_add_f32 v[8:9], v[12:13], v[10:11]
	v_mul_f32_e32 v10, v45, v45
	v_mul_f32_e32 v12, v47, v47
	v_pk_add_f32 v[8:9], v[8:9], v[8:9] op_sel:[0,1] op_sel_hi:[1,0]
	v_pk_fma_f32 v[10:11], v[44:45], v[44:45], v[10:11] op_sel_hi:[1,1,0]
	v_pk_fma_f32 v[12:13], v[46:47], v[46:47], v[12:13] op_sel_hi:[1,1,0]
	v_mul_f32_e32 v7, v48, v48
	v_mul_f32_e32 v9, v49, v49
	v_mul_f32_e32 v11, v50, v50
	v_mul_f32_e32 v13, v51, v51
	v_pk_add_f32 v[6:7], v[6:7], v[8:9]
	v_pk_add_f32 v[8:9], v[10:11], v[12:13]
	v_pk_mul_f32 v[10:11], v[52:53], v[52:53]
	v_pk_add_f32 v[6:7], v[6:7], v[8:9]
	v_pk_mul_f32 v[8:9], v[54:55], v[54:55]
	v_pk_add_f32 v[6:7], v[6:7], v[6:7] op_sel:[0,1] op_sel_hi:[1,0]
	v_pk_mov_b32 v[12:13], v[10:11], v[8:9] op_sel:[1,0]
	v_mov_b32_e32 v11, v9
	v_pk_add_f32 v[8:9], v[12:13], v[10:11]
	v_mul_f32_e32 v10, v57, v57
	v_mul_f32_e32 v12, v59, v59
	v_pk_add_f32 v[8:9], v[8:9], v[8:9] op_sel:[0,1] op_sel_hi:[1,0]
	v_pk_fma_f32 v[10:11], v[56:57], v[56:57], v[10:11] op_sel_hi:[1,1,0]
	v_pk_fma_f32 v[12:13], v[58:59], v[58:59], v[12:13] op_sel_hi:[1,1,0]
	v_mul_f32_e32 v7, v60, v60
	v_mul_f32_e32 v9, v61, v61
	v_mul_f32_e32 v11, v62, v62
	v_mul_f32_e32 v13, v63, v63
	v_pk_add_f32 v[6:7], v[6:7], v[8:9]
	v_pk_add_f32 v[8:9], v[10:11], v[12:13]
	v_pk_mul_f32 v[10:11], v[64:65], v[64:65]
	v_pk_add_f32 v[6:7], v[6:7], v[8:9]
	v_pk_mul_f32 v[8:9], v[66:67], v[66:67]
	v_pk_add_f32 v[6:7], v[6:7], v[6:7] op_sel:[0,1] op_sel_hi:[1,0]
	v_pk_mov_b32 v[12:13], v[10:11], v[8:9] op_sel:[1,0]
	v_mov_b32_e32 v11, v9
	v_pk_add_f32 v[8:9], v[12:13], v[10:11]
	v_mul_f32_e32 v10, v69, v69
	v_mul_f32_e32 v12, v71, v71
	v_pk_add_f32 v[8:9], v[8:9], v[8:9] op_sel:[0,1] op_sel_hi:[1,0]
	v_pk_fma_f32 v[10:11], v[68:69], v[68:69], v[10:11] op_sel_hi:[1,1,0]
	v_pk_fma_f32 v[12:13], v[70:71], v[70:71], v[12:13] op_sel_hi:[1,1,0]
	v_mul_f32_e32 v7, v2, v2
	v_mul_f32_e32 v9, v3, v3
	v_mul_f32_e32 v11, v4, v4
	v_mul_f32_e32 v13, v5, v5
	v_cvt_pk_bf16_f32 v2, v2, v3
	v_cvt_pk_bf16_f32 v3, v4, v5
	v_pk_add_f32 v[4:5], v[6:7], v[8:9]
	v_pk_add_f32 v[6:7], v[10:11], v[12:13]
	s_nop 0
	v_pk_add_f32 v[4:5], v[4:5], v[6:7]
	s_nop 0
	v_add_f32_e32 v4, v4, v5
	s_cbranch_execnz .LBB0_296

; #define GAS __attribute__((address_space(1)))
; __global__ void __launch_bounds__(NTHR, 2) fwd_kernel(Args args) {
;     ...
;         f32x4 v[16]; float s = 0.f;
;         if (m >= 256 && m < 16640) {
; #pragma unroll
;             for (int j = 0; j < 16; ++j) v[j] = yr[64 * j];
;         } else { const int slot = m < 256 ? m : 256 + (m - 16640);
; #pragma unroll
;             for (int j = 0; j < 16; ++j) { const v2u hw = *((const GAS v2u*)(H1B + (size_t)m * 4096) + lane + 64 * j); f32x4 a; a.x = __builtin_bit_cast(float, hw.x << 16); a.y = __builtin_bit_cast(float, hw.x & 0xffff0000u); a.z = __builtin_bit_cast(float, hw.y << 16); a.w = __builtin_bit_cast(float, hw.y & 0xffff0000u);
; #pragma unroll
;                 for (int ks = 0; ks < 8; ++ks) a = a + *((const GAS f32x4*)(SLAB + ((size_t)ks * 512 + slot) * 4096) + lane + 64 * j);
;                 v[j] = a; } }
; #pragma unroll
;         for (int j = 0; j < 16; ++j) s += (v[j].x * v[j].x + v[j].y * v[j].y) + (v[j].z * v[j].z + v[j].w * v[j].w);
;         s = wave_sum(s);
;         const float sc = 1.f / sqrtf(s * (1.f / 4096.f) + EPS);
.LBB0_3607:
	s_waitcnt vmcnt(15)
	v_mul_f32_e32 v66, v1, v1
	v_mul_f32_e32 v67, v3, v3
	v_fmac_f32_e32 v66, v0, v0
	v_fmac_f32_e32 v67, v2, v2
	v_add_f32_e32 v66, v66, v67
	s_waitcnt vmcnt(14)
	v_mul_f32_e32 v67, v5, v5
	v_mul_f32_e32 v68, v7, v7
	v_fmac_f32_e32 v67, v4, v4
	v_fmac_f32_e32 v68, v6, v6
	v_add_f32_e32 v67, v67, v68
	v_add_f32_e32 v66, v66, v67
	s_waitcnt vmcnt(13)
	v_mul_f32_e32 v67, v9, v9
	v_mul_f32_e32 v68, v11, v11
	v_fmac_f32_e32 v67, v8, v8
	v_fmac_f32_e32 v68, v10, v10
	v_add_f32_e32 v67, v67, v68
	v_add_f32_e32 v66, v66, v67
	s_waitcnt vmcnt(12)
	v_mul_f32_e32 v67, v13, v13
	v_mul_f32_e32 v68, v15, v15
	v_fmac_f32_e32 v67, v12, v12
	v_fmac_f32_e32 v68, v14, v14
	v_add_f32_e32 v67, v67, v68
	v_add_f32_e32 v66, v66, v67
	s_waitcnt vmcnt(11)
	v_mul_f32_e32 v67, v17, v17
	v_mul_f32_e32 v68, v19, v19
	v_fmac_f32_e32 v67, v16, v16
	v_fmac_f32_e32 v68, v18, v18
	v_add_f32_e32 v67, v67, v68
	v_add_f32_e32 v66, v66, v67
	s_waitcnt vmcnt(10)
	v_mul_f32_e32 v67, v21, v21
	v_mul_f32_e32 v68, v23, v23
	v_fmac_f32_e32 v67, v20, v20
	v_fmac_f32_e32 v68, v22, v22
	v_add_f32_e32 v67, v67, v68
	v_add_f32_e32 v66, v66, v67
	s_waitcnt vmcnt(9)
	v_mul_f32_e32 v67, v25, v25
	v_mul_f32_e32 v68, v27, v27
	v_fmac_f32_e32 v67, v24, v24
	v_fmac_f32_e32 v68, v26, v26
	v_add_f32_e32 v67, v67, v68
	v_add_f32_e32 v66, v66, v67
	s_waitcnt vmcnt(8)
	v_mul_f32_e32 v67, v29, v29
	v_mul_f32_e32 v68, v31, v31
	v_fmac_f32_e32 v67, v28, v28
	v_fmac_f32_e32 v68, v30, v30
	v_add_f32_e32 v67, v67, v68
	v_add_f32_e32 v66, v66, v67
	s_waitcnt vmcnt(7)
	v_mul_f32_e32 v67, v33, v33
	v_mul_f32_e32 v68, v35, v35
	v_fmac_f32_e32 v67, v32, v32
	v_fmac_f32_e32 v68, v34, v34
	v_add_f32_e32 v67, v67, v68
	v_add_f32_e32 v66, v66, v67
	s_waitcnt vmcnt(6)
	v_mul_f32_e32 v67, v37, v37
	v_mul_f32_e32 v68, v39, v39
	v_fmac_f32_e32 v67, v36, v36
	v_fmac_f32_e32 v68, v38, v38
	v_add_f32_e32 v67, v67, v68
	v_add_f32_e32 v66, v66, v67
	s_waitcnt vmcnt(5)
	v_mul_f32_e32 v67, v41, v41
	v_mul_f32_e32 v68, v43, v43
	v_fmac_f32_e32 v67, v40, v40
	v_fmac_f32_e32 v68, v42, v42
	v_add_f32_e32 v67, v67, v68
	v_add_f32_e32 v70, v66, v67
	global_load_dwordx4 v[66:69], v[90:91], off
	s_waitcnt vmcnt(5)
	v_mul_f32_e32 v71, v45, v45
	v_mul_f32_e32 v72, v47, v47
	v_fmac_f32_e32 v71, v44, v44
	v_fmac_f32_e32 v72, v46, v46
	v_add_f32_e32 v71, v71, v72
	v_add_f32_e32 v70, v70, v71
	s_waitcnt vmcnt(4)
	v_mul_f32_e32 v71, v49, v49
	v_mul_f32_e32 v72, v51, v51
	v_fmac_f32_e32 v71, v48, v48
	v_fmac_f32_e32 v72, v50, v50
	v_add_f32_e32 v71, v71, v72
	v_add_f32_e32 v70, v70, v71
	s_waitcnt vmcnt(3)
	v_mul_f32_e32 v71, v53, v53
	v_mul_f32_e32 v72, v55, v55
	v_fmac_f32_e32 v71, v52, v52
	v_fmac_f32_e32 v72, v54, v54
	v_add_f32_e32 v71, v71, v72
	v_add_f32_e32 v70, v70, v71
	s_waitcnt vmcnt(2)
	v_mul_f32_e32 v71, v57, v57
	v_mul_f32_e32 v72, v59, v59
	v_fmac_f32_e32 v71, v56, v56
	v_fmac_f32_e32 v72, v58, v58
	v_add_f32_e32 v71, v71, v72
	v_add_f32_e32 v70, v70, v71
	s_waitcnt vmcnt(1)
	v_mul_f32_e32 v71, v61, v61
	v_mul_f32_e32 v72, v63, v63
	v_fmac_f32_e32 v71, v60, v60
	v_fmac_f32_e32 v72, v62, v62
	v_add_f32_e32 v71, v71, v72
	v_add_f32_e32 v70, v70, v71
	global_load_dwordx4 v[160:163], v[90:91], off offset:1024
	global_load_dwordx4 v[164:167], v[90:91], off offset:2048
	global_load_dwordx4 v[168:171], v[90:91], off offset:3072
	global_load_dwordx4 v[172:175], v[120:121], off
	global_load_dwordx4 v[176:179], v[122:123], off
	global_load_dwordx4 v[180:183], v[124:125], off
	global_load_dwordx4 v[184:187], v[126:127], off
	global_load_dwordx4 v[188:191], v[128:129], off
	global_load_dwordx4 v[192:195], v[130:131], off
	global_load_dwordx4 v[196:199], v[132:133], off
	global_load_dwordx4 v[200:203], v[134:135], off
	global_load_dwordx4 v[204:207], v[136:137], off
	global_load_dwordx4 v[208:211], v[138:139], off
	global_load_dwordx4 v[212:215], v[140:141], off
	global_load_dwordx4 v[216:219], v[142:143], off
	v_mov_b32_e32 v71, v89
	s_nop 0
	v_add_f32_dpp v70, v70, v70 quad_perm:[1,0,3,2] row_mask:0xf bank_mask:0xf bound_ctrl:1
	s_nop 1
	v_add_f32_dpp v70, v70, v70 quad_perm:[2,3,0,1] row_mask:0xf bank_mask:0xf bound_ctrl:1
	s_nop 1
	v_add_f32_dpp v70, v70, v70 row_half_mirror row_mask:0xf bank_mask:0xf bound_ctrl:1
	s_nop 1
	v_add_f32_dpp v70, v70, v70 row_mirror row_mask:0xf bank_mask:0xf bound_ctrl:1
	s_nop 1
	v_mov_b32_dpp v71, v70 row_bcast:15 row_mask:0xa bank_mask:0xf
	v_add_f32_e32 v70, v70, v71
	v_mov_b32_e32 v71, v89
	s_nop 1
	v_mov_b32_dpp v71, v70 row_bcast:31 row_mask:0xc bank_mask:0xf
	v_add_f32_e32 v70, v70, v71
	s_nop 0
	v_readlane_b32 s0, v70, 63
	s_nop 1
	v_fma_f32 v70, s0, v154, v152
	v_mul_f32_e32 v71, 0x4f800000, v70
	v_cmp_gt_f32_e32 vcc, s26, v70
	s_nop 1
	v_cndmask_b32_e32 v70, v70, v71, vcc
	v_sqrt_f32_e32 v71, v70
	s_nop 0
	v_add_u32_e32 v72, -1, v71
	v_fma_f32 v73, -v72, v71, v70
	v_cmp_ge_f32_e64 s[0:1], 0, v73
	v_add_u32_e32 v73, 1, v71
	s_nop 0
	v_cndmask_b32_e64 v72, v71, v72, s[0:1]
	v_fma_f32 v71, -v73, v71, v70
	v_cmp_lt_f32_e64 s[0:1], 0, v71
	s_nop 1
	v_cndmask_b32_e64 v71, v72, v73, s[0:1]
	v_mul_f32_e32 v72, 0x37800000, v71
	v_cndmask_b32_e32 v71, v71, v72, vcc
	v_cmp_class_f32_e32 vcc, v70, v153
	s_nop 1
	v_cndmask_b32_e32 v70, v71, v70, vcc
	v_div_scale_f32 v71, s[0:1], v70, v70, 1.0
	v_rcp_f32_e32 v72, v71
	s_nop 0
	v_fma_f32 v73, -v71, v72, 1.0
	v_fmac_f32_e32 v72, v73, v72
	v_div_scale_f32 v73, vcc, 1.0, v70, 1.0
	v_mul_f32_e32 v74, v73, v72
	v_fma_f32 v75, -v71, v74, v73
	v_fmac_f32_e32 v74, v75, v72
	v_fma_f32 v71, -v71, v74, v73
	v_div_fmas_f32 v71, v71, v72, v74
	v_div_fixup_f32 v70, v71, v70, 1.0
	v_pk_mul_f32 v[0:1], v[70:71], v[0:1] op_sel_hi:[0,1]
	v_pk_mul_f32 v[2:3], v[70:71], v[2:3] op_sel_hi:[0,1]
	s_waitcnt vmcnt(0)
; __global__ void __launch_bounds__(NTHR, 2) fwd_kernel(Args args) {
;     ...
; #pragma unroll
;         for (int j = 0; j < 16; ++j) { const f32x4 gg = gf[64 * j]; yr[64 * j] = v[j] * sc * gg; }
	v_pk_mul_f32 v[2:3], v[68:69], v[2:3]
	v_pk_mul_f32 v[0:1], v[66:67], v[0:1]
	global_store_dwordx4 v[64:65], v[0:3], off nt
	v_pk_mul_f32 v[6:7], v[70:71], v[6:7] op_sel_hi:[0,1]
	v_pk_mul_f32 v[4:5], v[70:71], v[4:5] op_sel_hi:[0,1]
	v_pk_mul_f32 v[0:1], v[160:161], v[4:5]
	v_pk_mul_f32 v[2:3], v[162:163], v[6:7]
	global_store_dwordx4 v[64:65], v[0:3], off offset:1024 nt
	v_pk_mul_f32 v[4:5], v[70:71], v[10:11] op_sel_hi:[0,1]
	v_pk_mul_f32 v[6:7], v[70:71], v[8:9] op_sel_hi:[0,1]
	v_pk_mul_f32 v[8:9], v[70:71], v[16:17] op_sel_hi:[0,1]
	v_pk_mul_f32 v[10:11], v[70:71], v[20:21] op_sel_hi:[0,1]
	v_pk_mul_f32 v[0:1], v[164:165], v[6:7]
	v_pk_mul_f32 v[2:3], v[166:167], v[4:5]
	global_store_dwordx4 v[64:65], v[0:3], off offset:2048 nt
	v_pk_mul_f32 v[4:5], v[70:71], v[14:15] op_sel_hi:[0,1]
	v_pk_mul_f32 v[6:7], v[70:71], v[12:13] op_sel_hi:[0,1]
	v_pk_mul_f32 v[0:1], v[168:169], v[6:7]
	v_pk_mul_f32 v[2:3], v[170:171], v[4:5]
	global_store_dwordx4 v[64:65], v[0:3], off offset:3072 nt
	v_add_co_u32_e32 v4, vcc, s24, v64
	v_pk_mul_f32 v[6:7], v[70:71], v[18:19] op_sel_hi:[0,1]
	s_nop 0
	v_addc_co_u32_e32 v5, vcc, 0, v65, vcc
	v_pk_mul_f32 v[0:1], v[172:173], v[8:9]
	v_pk_mul_f32 v[2:3], v[174:175], v[6:7]
	global_store_dwordx4 v[4:5], v[0:3], off offset:-4096 nt
	v_add_co_u32_e32 v6, vcc, s23, v64
	v_pk_mul_f32 v[8:9], v[70:71], v[22:23] op_sel_hi:[0,1]
	s_nop 0
	v_addc_co_u32_e32 v7, vcc, 0, v65, vcc
	v_pk_mul_f32 v[0:1], v[176:177], v[10:11]
	v_pk_mul_f32 v[2:3], v[178:179], v[8:9]
	global_store_dwordx4 v[6:7], v[0:3], off offset:1024 nt
	v_pk_mul_f32 v[8:9], v[70:71], v[26:27] op_sel_hi:[0,1]
	v_pk_mul_f32 v[10:11], v[70:71], v[24:25] op_sel_hi:[0,1]
	v_pk_mul_f32 v[0:1], v[180:181], v[10:11]
	v_pk_mul_f32 v[2:3], v[182:183], v[8:9]
	global_store_dwordx4 v[6:7], v[0:3], off offset:2048 nt
	v_pk_mul_f32 v[8:9], v[70:71], v[30:31] op_sel_hi:[0,1]
	v_pk_mul_f32 v[10:11], v[70:71], v[28:29] op_sel_hi:[0,1]
	v_pk_mul_f32 v[0:1], v[184:185], v[10:11]
	v_pk_mul_f32 v[2:3], v[186:187], v[8:9]
	global_store_dwordx4 v[6:7], v[0:3], off offset:3072 nt
	v_pk_mul_f32 v[6:7], v[70:71], v[34:35] op_sel_hi:[0,1]
	v_pk_mul_f32 v[8:9], v[70:71], v[32:33] op_sel_hi:[0,1]
	v_pk_mul_f32 v[0:1], v[188:189], v[8:9]
	v_pk_mul_f32 v[2:3], v[190:191], v[6:7]
	global_store_dwordx4 v[4:5], v[0:3], off nt
	v_pk_mul_f32 v[6:7], v[70:71], v[38:39] op_sel_hi:[0,1]
	v_pk_mul_f32 v[8:9], v[70:71], v[36:37] op_sel_hi:[0,1]
	v_pk_mul_f32 v[0:1], v[192:193], v[8:9]
	v_pk_mul_f32 v[2:3], v[194:195], v[6:7]
	global_store_dwordx4 v[4:5], v[0:3], off offset:1024 nt
	v_pk_mul_f32 v[6:7], v[70:71], v[42:43] op_sel_hi:[0,1]
	v_pk_mul_f32 v[8:9], v[70:71], v[40:41] op_sel_hi:[0,1]
	v_pk_mul_f32 v[0:1], v[196:197], v[8:9]
	v_pk_mul_f32 v[2:3], v[198:199], v[6:7]
	global_store_dwordx4 v[4:5], v[0:3], off offset:2048 nt
	v_pk_mul_f32 v[6:7], v[70:71], v[46:47] op_sel_hi:[0,1]
	v_pk_mul_f32 v[8:9], v[70:71], v[44:45] op_sel_hi:[0,1]
	v_pk_mul_f32 v[0:1], v[200:201], v[8:9]
	v_pk_mul_f32 v[2:3], v[202:203], v[6:7]
	global_store_dwordx4 v[4:5], v[0:3], off offset:3072 nt
	v_add_co_u32_e32 v4, vcc, s25, v64
	v_pk_mul_f32 v[6:7], v[70:71], v[50:51] op_sel_hi:[0,1]
	v_pk_mul_f32 v[8:9], v[70:71], v[48:49] op_sel_hi:[0,1]
	v_addc_co_u32_e32 v5, vcc, 0, v65, vcc
	v_pk_mul_f32 v[0:1], v[204:205], v[8:9]
	v_pk_mul_f32 v[2:3], v[206:207], v[6:7]
	global_store_dwordx4 v[4:5], v[0:3], off nt
	v_pk_mul_f32 v[6:7], v[70:71], v[54:55] op_sel_hi:[0,1]
	v_pk_mul_f32 v[8:9], v[70:71], v[52:53] op_sel_hi:[0,1]
	v_pk_mul_f32 v[0:1], v[208:209], v[8:9]
	v_pk_mul_f32 v[2:3], v[210:211], v[6:7]
	global_store_dwordx4 v[4:5], v[0:3], off offset:1024 nt
	v_pk_mul_f32 v[6:7], v[70:71], v[58:59] op_sel_hi:[0,1]
	v_pk_mul_f32 v[8:9], v[70:71], v[56:57] op_sel_hi:[0,1]
	v_pk_mul_f32 v[0:1], v[212:213], v[8:9]
	v_pk_mul_f32 v[2:3], v[214:215], v[6:7]
	global_store_dwordx4 v[4:5], v[0:3], off offset:2048 nt
	v_pk_mul_f32 v[6:7], v[70:71], v[62:63] op_sel_hi:[0,1]
	v_pk_mul_f32 v[8:9], v[70:71], v[60:61] op_sel_hi:[0,1]
	v_pk_mul_f32 v[0:1], v[216:217], v[8:9]
	v_pk_mul_f32 v[2:3], v[218:219], v[6:7]
	global_store_dwordx4 v[4:5], v[0:3], off offset:3072 nt

; __global__ void __launch_bounds__(NTHR, 2) fwd_kernel(Args args) {
;     ...
;         if (m >= 256 && m < 16640) {
; #pragma unroll
;             for (int j = 0; j < 16; ++j) v[j] = yr[64 * j];
.LBB0_3617:
	v_add_co_u32_e32 v32, vcc, 0x1000, v64
	global_load_dwordx4 v[0:3], v[64:65], off nt
	global_load_dwordx4 v[4:7], v[64:65], off offset:1024 nt
	global_load_dwordx4 v[8:11], v[64:65], off offset:2048 nt
	global_load_dwordx4 v[12:15], v[64:65], off offset:3072 nt
	v_addc_co_u32_e32 v33, vcc, 0, v65, vcc
	v_add_co_u32_e32 v48, vcc, 0x2000, v64
	global_load_dwordx4 v[16:19], v[32:33], off nt
	global_load_dwordx4 v[20:23], v[32:33], off offset:1024 nt
	global_load_dwordx4 v[24:27], v[32:33], off offset:2048 nt
	global_load_dwordx4 v[28:31], v[32:33], off offset:3072 nt
	v_addc_co_u32_e32 v49, vcc, 0, v65, vcc
	v_add_co_u32_e32 v66, vcc, 0x3000, v64
	global_load_dwordx4 v[32:35], v[48:49], off nt
	global_load_dwordx4 v[36:39], v[48:49], off offset:1024 nt
	global_load_dwordx4 v[40:43], v[48:49], off offset:2048 nt
	global_load_dwordx4 v[44:47], v[48:49], off offset:3072 nt
	v_addc_co_u32_e32 v67, vcc, 0, v65, vcc
	global_load_dwordx4 v[48:51], v[66:67], off nt
	global_load_dwordx4 v[52:55], v[66:67], off offset:1024 nt
	global_load_dwordx4 v[56:59], v[66:67], off offset:2048 nt
	global_load_dwordx4 v[60:63], v[66:67], off offset:3072 nt
	s_branch .LBB0_3607
